# grid barrier: non-leader workgroups poll the top-level generation word directly (skips the per-XCD relay hop)
# speedup vs baseline: 1.0960x; 1.0045x over previous
.LBB0_261:
	s_or_b64 exec, exec, s[2:3]
	s_waitcnt vmcnt(0)
	v_readfirstlane_b32 s2, v1
	v_mul_lo_u32 v1, v196, s77
	s_nop 0
	v_add3_u32 v0, s2, v0, 1
	v_cmp_ne_u32_e32 vcc, v0, v1
	s_and_saveexec_b64 s[2:3], vcc
	s_xor_b64 s[2:3], exec, s[2:3]
	s_cbranch_execz .LBB0_284
	s_mov_b32 s26, 0x1000000
	s_mov_b64 s[4:5], 0
	v_readlane_b32 s100, v253, 18
	v_readlane_b32 s101, v253, 19
	s_nop 4
	s_branch .LBB0_272

.LBB0_272:
	global_load_dword v0, v195, s[100:101] sc1
	s_or_b64 s[6:7], s[6:7], exec
	s_waitcnt vmcnt(0)
	v_cmp_eq_u32_e32 vcc, v0, v245
	s_and_saveexec_b64 s[8:9], vcc
	s_cbranch_execz .LBB0_271
	s_cmp_lg_u32 s26, 0
	s_sleep 1
	s_cbranch_scc0 .LBB0_282
	global_load_dword v0, v195, s[100:101] sc1
	s_mov_b64 s[12:13], -1
	s_waitcnt vmcnt(0)
	v_cmp_eq_u32_e32 vcc, v0, v245
	s_and_saveexec_b64 s[10:11], vcc
	s_cbranch_execz .LBB0_269
	s_sleep 1
	global_load_dword v0, v195, s[100:101] sc1
	s_mov_b64 s[14:15], -1
	s_waitcnt vmcnt(0)
	v_cmp_eq_u32_e32 vcc, v0, v245
	s_and_saveexec_b64 s[12:13], vcc
	s_cbranch_execz .LBB0_268
	s_sleep 1
	global_load_dword v0, v195, s[100:101] sc1
	s_mov_b64 s[16:17], -1
	s_waitcnt vmcnt(0)
	v_cmp_eq_u32_e32 vcc, v0, v245
	s_and_saveexec_b64 s[14:15], vcc
	s_cbranch_execz .LBB0_267
	s_sleep 1
	global_load_dword v0, v195, s[100:101] sc1
	s_mov_b64 s[18:19], -1
	s_waitcnt vmcnt(0)
	v_cmp_eq_u32_e32 vcc, v0, v245
	s_and_saveexec_b64 s[16:17], vcc
	s_cbranch_execz .LBB0_266
	s_sleep 1
	global_load_dword v0, v195, s[100:101] sc1
	s_mov_b64 s[20:21], -1
	s_waitcnt vmcnt(0)
	v_cmp_eq_u32_e32 vcc, v0, v245
	s_and_saveexec_b64 s[18:19], vcc
	s_cbranch_execz .LBB0_265
	s_sleep 1
	global_load_dword v0, v195, s[100:101] sc1
	s_mov_b64 s[22:23], -1
	s_waitcnt vmcnt(0)
	v_cmp_eq_u32_e32 vcc, v0, v245
	s_and_saveexec_b64 s[20:21], vcc
	s_cbranch_execz .LBB0_264
	s_sleep 1
	global_load_dword v0, v195, s[100:101] sc1
	s_waitcnt vmcnt(0)
	v_cmp_eq_u32_e32 vcc, v0, v245
	s_and_saveexec_b64 s[24:25], vcc
	s_cbranch_execz .LBB0_263
	s_add_i32 s26, s26, -8
	s_xor_b64 s[22:23], exec, -1
	s_sleep 1
	s_branch .LBB0_263

.LBB0_371:
	s_or_b64 exec, exec, s[2:3]
	s_waitcnt vmcnt(0)
	v_readfirstlane_b32 s2, v1
	v_mul_lo_u32 v1, v109, s77
	s_nop 0
	v_add3_u32 v0, s2, v0, 1
	v_cmp_ne_u32_e32 vcc, v0, v1
	s_and_saveexec_b64 s[2:3], vcc
	s_xor_b64 s[2:3], exec, s[2:3]
	s_cbranch_execz .LBB0_394
	s_mov_b32 s26, 0x1000000
	s_mov_b64 s[4:5], 0
	v_readlane_b32 s100, v253, 18
	v_readlane_b32 s101, v253, 19
	s_nop 4
	s_branch .LBB0_382

.LBB0_382:
	global_load_dword v0, v195, s[100:101] sc1
	s_or_b64 s[6:7], s[6:7], exec
	s_waitcnt vmcnt(0)
	v_cmp_eq_u32_e32 vcc, v0, v196
	s_and_saveexec_b64 s[8:9], vcc
	s_cbranch_execz .LBB0_381
	s_cmp_lg_u32 s26, 0
	s_sleep 1
	s_cbranch_scc0 .LBB0_392
	global_load_dword v0, v195, s[100:101] sc1
	s_mov_b64 s[12:13], -1
	s_waitcnt vmcnt(0)
	v_cmp_eq_u32_e32 vcc, v0, v196
	s_and_saveexec_b64 s[10:11], vcc
	s_cbranch_execz .LBB0_379
	s_sleep 1
	global_load_dword v0, v195, s[100:101] sc1
	s_mov_b64 s[14:15], -1
	s_waitcnt vmcnt(0)
	v_cmp_eq_u32_e32 vcc, v0, v196
	s_and_saveexec_b64 s[12:13], vcc
	s_cbranch_execz .LBB0_378
	s_sleep 1
	global_load_dword v0, v195, s[100:101] sc1
	s_mov_b64 s[16:17], -1
	s_waitcnt vmcnt(0)
	v_cmp_eq_u32_e32 vcc, v0, v196
	s_and_saveexec_b64 s[14:15], vcc
	s_cbranch_execz .LBB0_377
	s_sleep 1
	global_load_dword v0, v195, s[100:101] sc1
	s_mov_b64 s[18:19], -1
	s_waitcnt vmcnt(0)
	v_cmp_eq_u32_e32 vcc, v0, v196
	s_and_saveexec_b64 s[16:17], vcc
	s_cbranch_execz .LBB0_376
	s_sleep 1
	global_load_dword v0, v195, s[100:101] sc1
	s_mov_b64 s[20:21], -1
	s_waitcnt vmcnt(0)
	v_cmp_eq_u32_e32 vcc, v0, v196
	s_and_saveexec_b64 s[18:19], vcc
	s_cbranch_execz .LBB0_375
	s_sleep 1
	global_load_dword v0, v195, s[100:101] sc1
	s_mov_b64 s[22:23], -1
	s_waitcnt vmcnt(0)
	v_cmp_eq_u32_e32 vcc, v0, v196
	s_and_saveexec_b64 s[20:21], vcc
	s_cbranch_execz .LBB0_374
	s_sleep 1
	global_load_dword v0, v195, s[100:101] sc1
	s_waitcnt vmcnt(0)
	v_cmp_eq_u32_e32 vcc, v0, v196
	s_and_saveexec_b64 s[24:25], vcc
	s_cbranch_execz .LBB0_373
	s_add_i32 s26, s26, -8
	s_xor_b64 s[22:23], exec, -1
	s_sleep 1
	s_branch .LBB0_373

.LBB0_610:
	s_or_b64 exec, exec, s[2:3]
	s_waitcnt vmcnt(0)
	v_readfirstlane_b32 s2, v1
	v_mul_lo_u32 v1, v41, s77
	s_nop 0
	v_add3_u32 v0, s2, v0, 1
	v_cmp_ne_u32_e32 vcc, v0, v1
	s_and_saveexec_b64 s[2:3], vcc
	s_xor_b64 s[2:3], exec, s[2:3]
	s_cbranch_execz .LBB0_633
	s_mov_b32 s26, 0x1000000
	s_mov_b64 s[4:5], 0
	v_readlane_b32 s100, v253, 18
	v_readlane_b32 s101, v253, 19
	s_nop 4
	s_branch .LBB0_621

.LBB0_621:
	global_load_dword v0, v195, s[100:101] sc1
	s_or_b64 s[6:7], s[6:7], exec
	s_waitcnt vmcnt(0)
	v_cmp_eq_u32_e32 vcc, v0, v109
	s_and_saveexec_b64 s[8:9], vcc
	s_cbranch_execz .LBB0_620
	s_cmp_lg_u32 s26, 0
	s_sleep 1
	s_cbranch_scc0 .LBB0_631
	global_load_dword v0, v195, s[100:101] sc1
	s_mov_b64 s[12:13], -1
	s_waitcnt vmcnt(0)
	v_cmp_eq_u32_e32 vcc, v0, v109
	s_and_saveexec_b64 s[10:11], vcc
	s_cbranch_execz .LBB0_618
	s_sleep 1
	global_load_dword v0, v195, s[100:101] sc1
	s_mov_b64 s[14:15], -1
	s_waitcnt vmcnt(0)
	v_cmp_eq_u32_e32 vcc, v0, v109
	s_and_saveexec_b64 s[12:13], vcc
	s_cbranch_execz .LBB0_617
	s_sleep 1
	global_load_dword v0, v195, s[100:101] sc1
	s_mov_b64 s[16:17], -1
	s_waitcnt vmcnt(0)
	v_cmp_eq_u32_e32 vcc, v0, v109
	s_and_saveexec_b64 s[14:15], vcc
	s_cbranch_execz .LBB0_616
	s_sleep 1
	global_load_dword v0, v195, s[100:101] sc1
	s_mov_b64 s[18:19], -1
	s_waitcnt vmcnt(0)
	v_cmp_eq_u32_e32 vcc, v0, v109
	s_and_saveexec_b64 s[16:17], vcc
	s_cbranch_execz .LBB0_615
	s_sleep 1
	global_load_dword v0, v195, s[100:101] sc1
	s_mov_b64 s[20:21], -1
	s_waitcnt vmcnt(0)
	v_cmp_eq_u32_e32 vcc, v0, v109
	s_and_saveexec_b64 s[18:19], vcc
	s_cbranch_execz .LBB0_614
	s_sleep 1
	global_load_dword v0, v195, s[100:101] sc1
	s_mov_b64 s[22:23], -1
	s_waitcnt vmcnt(0)
	v_cmp_eq_u32_e32 vcc, v0, v109
	s_and_saveexec_b64 s[20:21], vcc
	s_cbranch_execz .LBB0_613
	s_sleep 1
	global_load_dword v0, v195, s[100:101] sc1
	s_waitcnt vmcnt(0)
	v_cmp_eq_u32_e32 vcc, v0, v109
	s_and_saveexec_b64 s[24:25], vcc
	s_cbranch_execz .LBB0_612
	s_add_i32 s26, s26, -8
	s_xor_b64 s[22:23], exec, -1
	s_sleep 1
	s_branch .LBB0_612

.LBB0_692:
	s_or_b64 exec, exec, s[2:3]
	s_waitcnt vmcnt(0)
	v_readfirstlane_b32 s2, v1
	v_mul_lo_u32 v1, v193, s77
	s_nop 0
	v_add3_u32 v0, s2, v0, 1
	v_cmp_ne_u32_e32 vcc, v0, v1
	s_and_saveexec_b64 s[2:3], vcc
	s_xor_b64 s[2:3], exec, s[2:3]
	s_cbranch_execz .LBB0_715
	s_mov_b32 s26, 0x1000000
	s_mov_b64 s[4:5], 0
	v_readlane_b32 s100, v253, 18
	v_readlane_b32 s101, v253, 19
	s_nop 4
	s_branch .LBB0_703

.LBB0_703:
	global_load_dword v0, v195, s[100:101] sc1
	s_or_b64 s[6:7], s[6:7], exec
	s_waitcnt vmcnt(0)
	v_cmp_eq_u32_e32 vcc, v0, v41
	s_and_saveexec_b64 s[8:9], vcc
	s_cbranch_execz .LBB0_702
	s_cmp_lg_u32 s26, 0
	s_sleep 1
	s_cbranch_scc0 .LBB0_713
	global_load_dword v0, v195, s[100:101] sc1
	s_mov_b64 s[12:13], -1
	s_waitcnt vmcnt(0)
	v_cmp_eq_u32_e32 vcc, v0, v41
	s_and_saveexec_b64 s[10:11], vcc
	s_cbranch_execz .LBB0_700
	s_sleep 1
	global_load_dword v0, v195, s[100:101] sc1
	s_mov_b64 s[14:15], -1
	s_waitcnt vmcnt(0)
	v_cmp_eq_u32_e32 vcc, v0, v41
	s_and_saveexec_b64 s[12:13], vcc
	s_cbranch_execz .LBB0_699
	s_sleep 1
	global_load_dword v0, v195, s[100:101] sc1
	s_mov_b64 s[16:17], -1
	s_waitcnt vmcnt(0)
	v_cmp_eq_u32_e32 vcc, v0, v41
	s_and_saveexec_b64 s[14:15], vcc
	s_cbranch_execz .LBB0_698
	s_sleep 1
	global_load_dword v0, v195, s[100:101] sc1
	s_mov_b64 s[18:19], -1
	s_waitcnt vmcnt(0)
	v_cmp_eq_u32_e32 vcc, v0, v41
	s_and_saveexec_b64 s[16:17], vcc
	s_cbranch_execz .LBB0_697
	s_sleep 1
	global_load_dword v0, v195, s[100:101] sc1
	s_mov_b64 s[20:21], -1
	s_waitcnt vmcnt(0)
	v_cmp_eq_u32_e32 vcc, v0, v41
	s_and_saveexec_b64 s[18:19], vcc
	s_cbranch_execz .LBB0_696
	s_sleep 1
	global_load_dword v0, v195, s[100:101] sc1
	s_mov_b64 s[22:23], -1
	s_waitcnt vmcnt(0)
	v_cmp_eq_u32_e32 vcc, v0, v41
	s_and_saveexec_b64 s[20:21], vcc
	s_cbranch_execz .LBB0_695
	s_sleep 1
	global_load_dword v0, v195, s[100:101] sc1
	s_waitcnt vmcnt(0)
	v_cmp_eq_u32_e32 vcc, v0, v41
	s_and_saveexec_b64 s[24:25], vcc
	s_cbranch_execz .LBB0_694
	s_add_i32 s26, s26, -8
	s_xor_b64 s[22:23], exec, -1
	s_sleep 1
	s_branch .LBB0_694

.LBB0_797:
	s_or_b64 exec, exec, s[2:3]
	s_waitcnt vmcnt(0)
	v_readfirstlane_b32 s2, v1
	v_mul_lo_u32 v1, v157, s77
	s_nop 0
	v_add3_u32 v0, s2, v0, 1
	v_cmp_ne_u32_e32 vcc, v0, v1
	s_and_saveexec_b64 s[2:3], vcc
	s_xor_b64 s[2:3], exec, s[2:3]
	s_cbranch_execz .LBB0_820
	s_mov_b32 s26, 0x1000000
	s_mov_b64 s[4:5], 0
	v_readlane_b32 s100, v253, 18
	v_readlane_b32 s101, v253, 19
	s_nop 4
	s_branch .LBB0_808

.LBB0_808:
	global_load_dword v0, v195, s[100:101] sc1
	s_or_b64 s[6:7], s[6:7], exec
	s_waitcnt vmcnt(0)
	v_cmp_eq_u32_e32 vcc, v0, v193
	s_and_saveexec_b64 s[8:9], vcc
	s_cbranch_execz .LBB0_807
	s_cmp_lg_u32 s26, 0
	s_sleep 1
	s_cbranch_scc0 .LBB0_818
	global_load_dword v0, v195, s[100:101] sc1
	s_mov_b64 s[12:13], -1
	s_waitcnt vmcnt(0)
	v_cmp_eq_u32_e32 vcc, v0, v193
	s_and_saveexec_b64 s[10:11], vcc
	s_cbranch_execz .LBB0_805
	s_sleep 1
	global_load_dword v0, v195, s[100:101] sc1
	s_mov_b64 s[14:15], -1
	s_waitcnt vmcnt(0)
	v_cmp_eq_u32_e32 vcc, v0, v193
	s_and_saveexec_b64 s[12:13], vcc
	s_cbranch_execz .LBB0_804
	s_sleep 1
	global_load_dword v0, v195, s[100:101] sc1
	s_mov_b64 s[16:17], -1
	s_waitcnt vmcnt(0)
	v_cmp_eq_u32_e32 vcc, v0, v193
	s_and_saveexec_b64 s[14:15], vcc
	s_cbranch_execz .LBB0_803
	s_sleep 1
	global_load_dword v0, v195, s[100:101] sc1
	s_mov_b64 s[18:19], -1
	s_waitcnt vmcnt(0)
	v_cmp_eq_u32_e32 vcc, v0, v193
	s_and_saveexec_b64 s[16:17], vcc
	s_cbranch_execz .LBB0_802
	s_sleep 1
	global_load_dword v0, v195, s[100:101] sc1
	s_mov_b64 s[20:21], -1
	s_waitcnt vmcnt(0)
	v_cmp_eq_u32_e32 vcc, v0, v193
	s_and_saveexec_b64 s[18:19], vcc
	s_cbranch_execz .LBB0_801
	s_sleep 1
	global_load_dword v0, v195, s[100:101] sc1
	s_mov_b64 s[22:23], -1
	s_waitcnt vmcnt(0)
	v_cmp_eq_u32_e32 vcc, v0, v193
	s_and_saveexec_b64 s[20:21], vcc
	s_cbranch_execz .LBB0_800
	s_sleep 1
	global_load_dword v0, v195, s[100:101] sc1
	s_waitcnt vmcnt(0)
	v_cmp_eq_u32_e32 vcc, v0, v193
	s_and_saveexec_b64 s[24:25], vcc
	s_cbranch_execz .LBB0_799
	s_add_i32 s26, s26, -8
	s_xor_b64 s[22:23], exec, -1
	s_sleep 1
	s_branch .LBB0_799

.LBB0_1000:
	global_load_dword v0, v195, s[100:101] sc1
	s_or_b64 s[6:7], s[6:7], exec
	s_waitcnt vmcnt(0)
	v_cmp_eq_u32_e32 vcc, v0, v157
	s_and_saveexec_b64 s[8:9], vcc
	s_cbranch_execz .LBB0_999
	s_cmp_lg_u32 s26, 0
	s_sleep 1
	s_cbranch_scc0 .LBB0_1010
	global_load_dword v0, v195, s[100:101] sc1
	s_mov_b64 s[12:13], -1
	s_waitcnt vmcnt(0)
	v_cmp_eq_u32_e32 vcc, v0, v157
	s_and_saveexec_b64 s[10:11], vcc
	s_cbranch_execz .LBB0_997
	s_sleep 1
	global_load_dword v0, v195, s[100:101] sc1
	s_mov_b64 s[14:15], -1
	s_waitcnt vmcnt(0)
	v_cmp_eq_u32_e32 vcc, v0, v157
	s_and_saveexec_b64 s[12:13], vcc
	s_cbranch_execz .LBB0_996
	s_sleep 1
	global_load_dword v0, v195, s[100:101] sc1
	s_mov_b64 s[16:17], -1
	s_waitcnt vmcnt(0)
	v_cmp_eq_u32_e32 vcc, v0, v157
	s_and_saveexec_b64 s[14:15], vcc
	s_cbranch_execz .LBB0_995
	s_sleep 1
	global_load_dword v0, v195, s[100:101] sc1
	s_mov_b64 s[18:19], -1
	s_waitcnt vmcnt(0)
	v_cmp_eq_u32_e32 vcc, v0, v157
	s_and_saveexec_b64 s[16:17], vcc
	s_cbranch_execz .LBB0_994
	s_sleep 1
	global_load_dword v0, v195, s[100:101] sc1
	s_mov_b64 s[20:21], -1
	s_waitcnt vmcnt(0)
	v_cmp_eq_u32_e32 vcc, v0, v157
	s_and_saveexec_b64 s[18:19], vcc
	s_cbranch_execz .LBB0_993
	s_sleep 1
	global_load_dword v0, v195, s[100:101] sc1
	s_mov_b64 s[22:23], -1
	s_waitcnt vmcnt(0)
	v_cmp_eq_u32_e32 vcc, v0, v157
	s_and_saveexec_b64 s[20:21], vcc
	s_cbranch_execz .LBB0_992
	s_sleep 1
	global_load_dword v0, v195, s[100:101] sc1
	s_waitcnt vmcnt(0)
	v_cmp_eq_u32_e32 vcc, v0, v157
	s_and_saveexec_b64 s[24:25], vcc
	s_cbranch_execz .LBB0_991
	s_add_i32 s26, s26, -8
	s_xor_b64 s[22:23], exec, -1
	s_sleep 1
	s_branch .LBB0_991

.LBB0_1096:
	s_or_b64 exec, exec, s[2:3]
	s_waitcnt vmcnt(0)
	v_readfirstlane_b32 s2, v2
	v_mul_lo_u32 v2, v0, s77
	s_nop 0
	v_add3_u32 v1, s2, v1, 1
	v_cmp_ne_u32_e32 vcc, v1, v2
	s_and_saveexec_b64 s[2:3], vcc
	s_xor_b64 s[2:3], exec, s[2:3]
	s_cbranch_execz .LBB0_1119
	s_mov_b32 s28, 0x1000000
	s_mov_b64 s[6:7], 0
	v_readlane_b32 s100, v253, 18
	v_readlane_b32 s101, v253, 19
	s_nop 4
	s_branch .LBB0_1107

.LBB0_1107:
	global_load_dword v1, v195, s[100:101] sc1
	s_or_b64 s[8:9], s[8:9], exec
	s_waitcnt vmcnt(0)
	v_cmp_eq_u32_e32 vcc, v1, v193
	s_and_saveexec_b64 s[10:11], vcc
	s_cbranch_execz .LBB0_1106
	s_cmp_lg_u32 s28, 0
	s_sleep 1
	s_cbranch_scc0 .LBB0_1117
	global_load_dword v1, v195, s[100:101] sc1
	s_mov_b64 s[14:15], -1
	s_waitcnt vmcnt(0)
	v_cmp_eq_u32_e32 vcc, v1, v193
	s_and_saveexec_b64 s[12:13], vcc
	s_cbranch_execz .LBB0_1104
	s_sleep 1
	global_load_dword v1, v195, s[100:101] sc1
	s_mov_b64 s[16:17], -1
	s_waitcnt vmcnt(0)
	v_cmp_eq_u32_e32 vcc, v1, v193
	s_and_saveexec_b64 s[14:15], vcc
	s_cbranch_execz .LBB0_1103
	s_sleep 1
	global_load_dword v1, v195, s[100:101] sc1
	s_mov_b64 s[18:19], -1
	s_waitcnt vmcnt(0)
	v_cmp_eq_u32_e32 vcc, v1, v193
	s_and_saveexec_b64 s[16:17], vcc
	s_cbranch_execz .LBB0_1102
	s_sleep 1
	global_load_dword v1, v195, s[100:101] sc1
	s_mov_b64 s[20:21], -1
	s_waitcnt vmcnt(0)
	v_cmp_eq_u32_e32 vcc, v1, v193
	s_and_saveexec_b64 s[18:19], vcc
	s_cbranch_execz .LBB0_1101
	s_sleep 1
	global_load_dword v1, v195, s[100:101] sc1
	s_mov_b64 s[22:23], -1
	s_waitcnt vmcnt(0)
	v_cmp_eq_u32_e32 vcc, v1, v193
	s_and_saveexec_b64 s[20:21], vcc
	s_cbranch_execz .LBB0_1100
	s_sleep 1
	global_load_dword v1, v195, s[100:101] sc1
	s_mov_b64 s[24:25], -1
	s_waitcnt vmcnt(0)
	v_cmp_eq_u32_e32 vcc, v1, v193
	s_and_saveexec_b64 s[22:23], vcc
	s_cbranch_execz .LBB0_1099
	s_sleep 1
	global_load_dword v1, v195, s[100:101] sc1
	s_waitcnt vmcnt(0)
	v_cmp_eq_u32_e32 vcc, v1, v193
	s_and_saveexec_b64 s[26:27], vcc
	s_cbranch_execz .LBB0_1098
	s_add_i32 s28, s28, -8
	s_xor_b64 s[24:25], exec, -1
	s_sleep 1
	s_branch .LBB0_1098
